# sliding-window units re-shaped: 64 query positions x the kv head's 4 query heads per unit (wave = head, row group), 4 key tiles per unit instead of 6
# speedup vs baseline: 1.0067x; 1.0067x over previous
;   #define PIN(x) asm volatile("":"+v"(x))
; template<int THRL> __device__ __forceinline__ void attn_unit(long rowbase,int qb,int t0,bool WIN,bool NOMAX,const bf16*Qc,const bf16*__restrict__ Kc,const bf16*__restrict__ Vc,bf16*Oc,float s2,float sink2,char*shm,
;     bf16x8 (&qr)[4],bool pref,const bf16*qkvb,int vn,int in_){
;   int tid=threadIdx.x; asm volatile("":"+v"(tid)); const int lane=tid&63,r32=lane&31,hi=lane>>5; const int wid=__builtin_amdgcn_readfirstlane(tid>>6);
;   const int q0=qb*QB;
;   const bf16*Qw=Qc+(rowbase+q0+wid*QBLK)*PIN;
;   const bf16*Kh=Kc+(rowbase+(long)t0*KVBLK)*PIN,*Vh=Vc+(rowbase+(long)t0*KVBLK)*PIN;
; __global__ void __launch_bounds__(NWAVES * 64, 2) mk_fwd(Args args) {
;     ...
;                         const int ui = v * 4 + (i - 8), hq = (ui >> 5) & 7, b = ui >> 8; qb = ui & 31; t0 = qb > 0 ? 4 * qb - 2 : 0; win = true; rowbase = (long)b * SEQ;
;                         qc = hq * 64; kc = 512 + (hq >> 2) * 64; vc = 640 + (hq >> 2) * 64; oc = hq * 64; Ob = OA;
;                         s2 = exp2f(-8.0f * (float)(1 + hq) / 12.0f) * LOG2E; sink2 = ap->in[9][l * 8 + hq] * LOG2E;
;                     }
;                     int vn = v, in = i + 1; if (in == 12) { in = 0; vn = v + G; }
;                     if (vn >= 256) in = -1;
;                     attn_body::attn_unit<60>(rowbase, qb, t0, win, win ? nomax_swa : nomax_diff, (const attn_body::bf16*)QKV + qc, (const attn_body::bf16*)QKV + kc, (const attn_body::bf16*)QKV + vc, (attn_body::bf16*)Ob + oc, s2, sink2, (char*)lds,
.LBB0_257:
	s_lshl_b32 s4, s75, 2
	s_and_b32 s4, s4, 32
	s_add_i32 s4, s4, s77
	s_ashr_i32 s42, s4, 4
	s_mov_b32 s100, 0
	s_mov_b32 s101, 8
	s_mov_b64 s[44:45], 0
.LBB0_258:
	s_xor_b64 s[40:41], s[38:39], -1
	s_and_b64 vcc, exec, s[44:45]
	v_mov_b32_e32 v235, 0xff800000
	v_mov_b32_e32 v51, v179
	s_mov_b64 s[52:53], s[56:57]
	v_mov_b32_e32 v34, v182
	s_mov_b32 s90, s33
	s_mov_b32 s38, s91
	s_mov_b32 s39, s89
	s_mov_b32 s49, s88
	s_cbranch_vccz .LBB0_260
	s_add_i32 s4, s3, s85
	s_and_b32 s2, s4, 127
	s_ashr_i32 s42, s4, 8
	s_bfe_u32 s43, s4, 0x10007
	s_add_i32 s38, s2, -3
	s_max_i32 s48, s38, 0
	v_readfirstlane_b32 s100, v234
	s_lshr_b32 s100, s100, 6
	s_lshl_b32 s4, s43, 6
	s_or_b32 s39, s4, 0x200
	s_or_b32 s38, s4, 0x280
	s_lshl_b32 s43, s43, 2
	s_and_b32 s101, s100, 3
	s_or_b32 s43, s43, s101
	s_not_b32 s4, s43
	s_lshl_b32 s4, s4, 3
	v_cvt_f32_i32_e32 v0, s4
	s_mov_b32 s4, 0x41400000
	s_lshl_b32 s90, s43, 6
	s_mov_b64 s[52:53], 0x13000000
	v_div_scale_f32 v2, s[44:45], s4, s4, v0
	v_rcp_f32_e32 v3, v2
	v_mov_b32_e32 v51, v178
	s_mov_b32 s49, s90
	v_fma_f32 v4, -v2, v3, 1.0
	v_fmac_f32_e32 v3, v4, v3
	v_div_scale_f32 v4, vcc, v0, s4, v0
	v_mul_f32_e32 v5, v4, v3
	v_fma_f32 v6, -v2, v5, v4
	v_fmac_f32_e32 v5, v6, v3
	v_fma_f32 v2, -v2, v5, v4
	v_div_fmas_f32 v2, v2, v3, v5
	v_div_fixup_f32 v0, v2, s4, v0
	s_mov_b32 s4, 0xc2fc0000
	v_cmp_gt_f32_e32 vcc, s4, v0
	s_and_b64 s[44:45], vcc, exec
	s_load_dwordx2 s[44:45], s[46:47], 0x48
	v_cndmask_b32_e32 v2, 0, v216, vcc
	v_add_f32_e32 v0, v0, v2
	v_exp_f32_e32 v0, v0
	s_cselect_b32 s4, 0xffffffc0, 0
	v_ldexp_f32 v34, v0, s4
	s_or_b32 s4, s43, s74
	s_lshl_b64 s[50:51], s[4:5], 2
	s_waitcnt lgkmcnt(0)
	s_add_u32 s44, s44, s50
	s_addc_u32 s45, s45, s51
	global_load_dword v0, v1, s[44:45]
	s_waitcnt vmcnt(0)
	v_mul_f32_e32 v235, 0x3fb8aa3b, v0
	s_mov_b32 s100, 2
	s_mov_b32 s101, 6
.LBB0_260:
	s_ashr_i32 s43, s42, 31
	s_lshl_b64 s[42:43], s[42:43], 13
	s_lshl_b32 s4, s39, 1
	s_add_u32 s39, s72, s4
	s_addc_u32 s50, s73, 0
	s_lshl_b32 s4, s38, 1
	v_mov_b32_e32 v50, v234
	s_add_u32 s51, s72, s4
	s_addc_u32 s60, s73, 0
	v_readfirstlane_b32 s44, v50
	s_ashr_i32 s80, s44, 6
	s_lshl_b32 s4, s2, s101
	s_add_u32 s38, s42, s4
	s_addc_u32 s45, s43, 0
	s_lshr_b32 s2, s80, s100
	s_lshl_b32 s2, s2, 5
	s_ashr_i32 s59, s2, 31
	s_add_u32 s58, s38, s2
	s_addc_u32 s59, s45, s59
	s_lshl_b32 s45, s48, 6
	s_add_u32 s38, s42, s45
	s_addc_u32 s42, s43, 0
	s_mulk_i32 s42, 0x1200
	s_mul_hi_u32 s43, s38, 0x1200
	s_add_i32 s43, s43, s42
	s_mul_i32 s42, s38, 0x1200
	s_add_u32 s38, s39, s42
	v_and_b32_e32 v183, 63, v50
	s_addc_u32 s39, s50, s43
	s_add_u32 s42, s51, s42
	v_mul_u32_u24_e32 v0, 0x900, v183
	s_addc_u32 s43, s60, s43
	v_lshlrev_b32_e32 v0, 1, v0
	s_lshl_b32 s60, s80, 3
	v_lshl_add_u64 v[2:3], s[38:39], 0, v[0:1]
	s_ashr_i32 s61, s60, 31
	v_lshl_add_u64 v[194:195], s[60:61], 1, v[2:3]
	s_lshl_b32 s38, s80, 4
	v_bfe_u32 v2, v50, 2, 4
	v_and_or_b32 v2, s38, 48, v2
	v_mul_u32_u24_e32 v2, 0x900, v2
	s_ashr_i32 s38, s44, 3
	v_lshlrev_b32_e32 v2, 1, v2
	v_mov_b32_e32 v3, v1
	s_andn2_b32 s38, s38, 31
	v_lshlrev_b32_e32 v233, 3, v50
	v_lshl_add_u64 v[2:3], s[42:43], 0, v[2:3]
	s_ashr_i32 s39, s38, 31
	v_and_b32_e32 v219, 24, v233
	s_lshl_b32 s82, s80, 10
	v_lshl_add_u64 v[2:3], s[38:39], 1, v[2:3]
	v_lshlrev_b32_e32 v4, 1, v219
	v_mov_b32_e32 v5, v1
	s_cmp_lg_u32 0, -1
	v_and_b32_e32 v180, 31, v50
	v_lshl_add_u64 v[82:83], v[2:3], 0, v[4:5]
	s_cselect_b32 s38, 0, 0
	v_cndmask_b32_e64 v2, 0, 1, s[40:41]
	s_add_i32 s50, s82, s38
	v_cmp_ne_u32_e64 s[38:39], 1, v2
	v_mul_u32_u24_e32 v2, 0x900, v180
	v_bfe_u32 v181, v50, 5, 1
	s_add_i32 s79, s50, 0x6000
	s_mov_b64 s[42:43], -1
	s_andn2_b64 vcc, exec, s[40:41]
	v_lshlrev_b32_e32 v222, 1, v2
	s_cbranch_vccz .LBB0_352
	s_andn2_b64 vcc, exec, s[42:43]
	s_cbranch_vccz .LBB0_353

; #define WAIT_BAR(N) asm volatile("s_waitcnt vmcnt(" #N ") lgkmcnt(0)\n\ts_barrier":::"memory")
;   #define DMA_K(t,slot) glds16(ksrc+(long)(t)*KVBLK*PIN,(unsigned)__builtin_amdgcn_readfirstlane(kdst+(slot)))
;   #define CINIT(C0,C1,btl) do{ const float b_=(btl); _Pragma("unroll") for(int r=0;r<16;++r){ C0[r]=__builtin_fmaf(s2,(float)((r&3)+8*(r>>2)),b_); C1[r]=__builtin_fmaf(s2,(float)((r&3)+8*(r>>2)+32),b_);} }while(0)
;   #define CMASK(P0,P1,t) do{ if(WIN||(t)>=NT-4)gmask(P0,P1,64*(t),qrel,hi,WIN);}while(0)
;   #define START(P0,P1) do{ resc=false; \
;     if(!NOMAX){ const float rm=rowmax(P0,P1); const float dl=__builtin_fmaxf(rm,0.f);     \
;       mhat=fadd_s(mhat,dl); \
;       _Pragma("unroll") for(int r=0;r<16;++r){P0[r]=fsub_s(P0[r],dl);P1[r]=fsub_s(P1[r],dl);} } \
;     _Pragma("unroll") for(int r=0;r<16;++r)P0[r]=__builtin_amdgcn_exp2f(P0[r]); }while(0)
;   #define CMASK(P0,P1,t) do{}while(0)
;   #define CMASK(P0,P1,t) do{ if(WIN||(t)>=NT-4)gmask(P0,P1,64*(t),qrel,hi,WIN);}while(0)
; template<int THRL> __device__ __forceinline__ void attn_unit(long rowbase,int qb,int t0,bool WIN,bool NOMAX,const bf16*Qc,const bf16*__restrict__ Kc,const bf16*__restrict__ Vc,bf16*Oc,float s2,float sink2,char*shm,
;     bf16x8 (&qr)[4],bool pref,const bf16*qkvb,int vn,int in_){
;     ...
;   const int qrel=q0-t0*KVBLK+wid*QBLK+r32;
;   const float qb2=s2*(float)(qrel-4*hi);
;     ...
;   bool resc=false;
;     ...
;   f32x16 pA0,pA1,pB0,pB1;
;   int sl_prev=0,sl_cur=0,sl_next=SLOTB;
;     ...
;   if(!pref){ DMA_K(2,2*SLOTB);
;     WAIT_BAR(3); }
;   else { WAIT_BAR(5); }
;   CINIT(pA0,pA1,-qb2); qkt(pA0,pA1,Kbase,qr,r32,hi);asm volatile("s_nop 15\n\ts_nop 7":"+v"(pA0),"+v"(pA1));CMASK(pA0,pA1,0);
;   START(pA0,pA1);
.LBB0_265:
	s_sub_i32 s38, s4, s45
	v_or_b32_e32 v18, s38, v180
	v_lshlrev_b32_e32 v230, 2, v181
	v_add_u32_e32 v223, s2, v18
	v_sub_u32_e32 v18, v223, v230
	v_cvt_f32_i32_e32 v19, v18
	v_lshlrev_b32_e32 v18, 10, v181
	v_lshlrev_b32_e32 v20, 4, v180
	v_add3_u32 v231, 0, v18, v20
	v_mul_f32_e32 v184, 0x3fb8aa3b, v34
	ds_read_b128 v[34:37], v231
	ds_read_b128 v[52:55], v231 offset:512
	v_mul_f32_e64 v186, v184, -v19
	v_fma_f32 v18, 0, v184, v186
	v_fma_f32 v19, v184, -v19, v184
	v_pk_fma_f32 v[20:21], v[184:185], s[8:9], v[186:187] op_sel_hi:[0,1,0]
	v_pk_fma_f32 v[22:23], v[184:185], s[10:11], v[186:187] op_sel_hi:[0,1,0]
	v_pk_fma_f32 v[24:25], v[184:185], s[12:13], v[186:187] op_sel_hi:[0,1,0]
	v_pk_fma_f32 v[26:27], v[184:185], s[14:15], v[186:187] op_sel_hi:[0,1,0]
	v_pk_fma_f32 v[28:29], v[184:185], s[16:17], v[186:187] op_sel_hi:[0,1,0]
	v_pk_fma_f32 v[30:31], v[184:185], s[18:19], v[186:187] op_sel_hi:[0,1,0]
	v_pk_fma_f32 v[32:33], v[184:185], s[20:21], v[186:187] op_sel_hi:[0,1,0]
	v_pk_fma_f32 v[48:49], v[184:185], s[22:23], v[186:187] op_sel_hi:[0,1,0]
	v_pk_fma_f32 v[46:47], v[184:185], s[24:25], v[186:187] op_sel_hi:[0,1,0]
	s_waitcnt vmcnt(3) lgkmcnt(1)
	v_mfma_f32_32x32x16_bf16 v[18:33], v[34:37], v[2:5], v[18:33]
	v_fma_f32 v44, v184, s26, v186
	v_fma_f32 v45, v184, s27, v186
	v_fma_f32 v42, v184, s28, v186
	v_fma_f32 v43, v184, s29, v186
	v_fma_f32 v40, v184, s30, v186
	v_fma_f32 v41, v184, s31, v186
	v_pk_fma_f32 v[38:39], v[184:185], s[34:35], v[186:187] op_sel_hi:[0,1,0]
	v_pk_fma_f32 v[36:37], v[184:185], s[36:37], v[186:187] op_sel_hi:[0,1,0]
	v_pk_fma_f32 v[34:35], v[184:185], s[92:93], v[186:187] op_sel_hi:[0,1,0]
	s_addk_i32 s4, 0x100
	s_lshr_b32 s4, s4, 6
	s_waitcnt lgkmcnt(0)
	v_mfma_f32_32x32x16_bf16 v[34:49], v[52:55], v[2:5], v[34:49]
	ds_read_b128 v[52:55], v231 offset:2048
	s_sub_i32 s4, s4, s48
	s_cmp_lg_u32 s62, 0
	s_cselect_b32 s4, 4, s4
	s_cmp_lt_i32 s4, 5
	s_cselect_b64 s[38:39], -1, 0
	s_or_b64 s[38:39], s[62:63], s[38:39]
	s_andn2_b64 vcc, exec, s[38:39]
	v_add_u32_e32 v224, 0xffffff80, v223
	s_waitcnt vmcnt(2) lgkmcnt(0)
	v_mfma_f32_32x32x16_bf16 v[18:33], v[52:55], v[6:9], v[18:33]
	ds_read_b128 v[52:55], v231 offset:2560
	s_waitcnt lgkmcnt(0)
	v_mfma_f32_32x32x16_bf16 v[34:49], v[52:55], v[6:9], v[34:49]
	ds_read_b128 v[52:55], v231 offset:4096
	s_waitcnt vmcnt(1) lgkmcnt(0)
	v_mfma_f32_32x32x16_bf16 v[18:33], v[52:55], v[10:13], v[18:33]
	ds_read_b128 v[52:55], v231 offset:4608
	s_waitcnt lgkmcnt(0)
	v_mfma_f32_32x32x16_bf16 v[34:49], v[52:55], v[10:13], v[34:49]
	ds_read_b128 v[52:55], v231 offset:6144
	s_waitcnt vmcnt(0) lgkmcnt(0)
	v_mfma_f32_32x32x16_bf16 v[18:33], v[52:55], v[14:17], v[18:33]
	ds_read_b128 v[52:55], v231 offset:6656
	s_waitcnt lgkmcnt(0)
	v_mfma_f32_32x32x16_bf16 v[34:49], v[52:55], v[14:17], v[34:49]
	v_cndmask_b32_e64 v52, 0, 1, s[62:63]
	v_cmp_ne_u32_e64 s[38:39], 1, v52
	s_nop 15
	s_nop 7
	s_cbranch_vccnz .LBB0_330
	v_sub_u32_e32 v52, v223, v230
	s_nop 0
	v_readfirstlane_b32 s40, v52
	s_cmp_gt_i32 s40, 66
	s_cbranch_scc1 .Lmy_mk_c_s0
	v_cmp_le_i32_e32 vcc, 0, v52
	v_cndmask_b32_e32 v18, v217, v18, vcc
	v_cmp_le_i32_e32 vcc, 32, v52
	v_cndmask_b32_e32 v34, v217, v34, vcc
	v_cmp_le_i32_e32 vcc, 1, v52
	v_cndmask_b32_e32 v19, v217, v19, vcc
	v_cmp_le_i32_e32 vcc, 33, v52
	v_cndmask_b32_e32 v35, v217, v35, vcc
	v_cmp_le_i32_e32 vcc, 2, v52
	v_cndmask_b32_e32 v20, v217, v20, vcc
	v_cmp_le_i32_e32 vcc, 34, v52
	v_cndmask_b32_e32 v36, v217, v36, vcc
	v_cmp_le_i32_e32 vcc, 3, v52
	v_cndmask_b32_e32 v21, v217, v21, vcc
	v_cmp_le_i32_e32 vcc, 35, v52
	v_cndmask_b32_e32 v37, v217, v37, vcc
	v_cmp_le_i32_e32 vcc, 8, v52
	v_cndmask_b32_e32 v22, v217, v22, vcc
	v_cmp_le_i32_e32 vcc, 40, v52
	v_cndmask_b32_e32 v38, v217, v38, vcc
	v_cmp_le_i32_e32 vcc, 9, v52
	v_cndmask_b32_e32 v23, v217, v23, vcc
	v_cmp_le_i32_e32 vcc, 41, v52
	v_cndmask_b32_e32 v39, v217, v39, vcc
	v_cmp_le_i32_e32 vcc, 10, v52
	v_cndmask_b32_e32 v24, v217, v24, vcc
	v_cmp_le_i32_e32 vcc, 42, v52
	v_cndmask_b32_e32 v40, v217, v40, vcc
	v_cmp_le_i32_e32 vcc, 11, v52
	v_cndmask_b32_e32 v25, v217, v25, vcc
	v_cmp_le_i32_e32 vcc, 43, v52
	v_cndmask_b32_e32 v41, v217, v41, vcc
	v_cmp_le_i32_e32 vcc, 16, v52
	v_cndmask_b32_e32 v26, v217, v26, vcc
	v_cmp_le_i32_e32 vcc, 48, v52
	v_cndmask_b32_e32 v42, v217, v42, vcc
	v_cmp_le_i32_e32 vcc, 17, v52
	v_cndmask_b32_e32 v27, v217, v27, vcc
	v_cmp_le_i32_e32 vcc, 49, v52
	v_cndmask_b32_e32 v43, v217, v43, vcc
	v_cmp_le_i32_e32 vcc, 18, v52
	v_cndmask_b32_e32 v28, v217, v28, vcc
	v_cmp_le_i32_e32 vcc, 50, v52
	v_cndmask_b32_e32 v44, v217, v44, vcc
	v_cmp_le_i32_e32 vcc, 19, v52
	v_cndmask_b32_e32 v29, v217, v29, vcc
	v_cmp_le_i32_e32 vcc, 51, v52
	v_cndmask_b32_e32 v45, v217, v45, vcc
	v_cmp_le_i32_e32 vcc, 24, v52
	v_cndmask_b32_e32 v30, v217, v30, vcc
	v_cmp_le_i32_e32 vcc, 56, v52
	v_cndmask_b32_e32 v46, v217, v46, vcc
	v_cmp_le_i32_e32 vcc, 25, v52
	v_cndmask_b32_e32 v31, v217, v31, vcc
	v_cmp_le_i32_e32 vcc, 57, v52
	v_cndmask_b32_e32 v47, v217, v47, vcc
	v_cmp_le_i32_e32 vcc, 26, v52
	v_cndmask_b32_e32 v32, v217, v32, vcc
	v_cmp_le_i32_e32 vcc, 58, v52
	v_cndmask_b32_e32 v48, v217, v48, vcc
	v_cmp_le_i32_e32 vcc, 27, v52
	v_cndmask_b32_e32 v33, v217, v33, vcc
	v_cmp_le_i32_e32 vcc, 59, v52
	v_cndmask_b32_e32 v49, v217, v49, vcc

;   #define PIN(x) asm volatile("":"+v"(x))
; __device__ __forceinline__ void unit_qk_offsets(int vv,int ii,long&qo,long&ko){
;   int q_,t_,qc_,kc_; long rb;
;   if(ii<8){ const int s=vv&7,bhv=(vv>>3)+32*(ii>>2),i4=ii&3,b=bhv>>4,h=(bhv>>2)&3,c=(bhv>>1)&1;
;     q_=(i4==0)?s:(i4==1)?15-s:(i4==2)?16+s:31-s; t_=0; rb=(long)b*SEQ; qc_=768+h*128+c*64; kc_=1280+h*128+c*64; }
;   else{ const int ui=vv*4+(ii-8),hq=(ui>>5)&7,b=ui>>8; q_=ui&31; t_=q_>0?4*q_-2:0; rb=(long)b*SEQ; qc_=hq*64; kc_=512+(hq>>2)*64; }
;   qo=qc_+(rb+(long)q_*QB)*PIN; ko=kc_+(rb+(long)t_*KVBLK)*PIN;
; }
; template<int THRL> __device__ __forceinline__ void attn_unit(long rowbase,int qb,int t0,bool WIN,bool NOMAX,const bf16*Qc,const bf16*__restrict__ Kc,const bf16*__restrict__ Vc,bf16*Oc,float s2,float sink2,char*shm,
;     bf16x8 (&qr)[4],bool pref,const bf16*qkvb,int vn,int in_){
;     ...
;   if(in_>=0){ long qo,ko; unit_qk_offsets(vn,in_,qo,ko);
;     const bf16*ksn=qkvb+ko+(long)lane*PIN+wid*8;
;     glds16(ksn,(unsigned)__builtin_amdgcn_readfirstlane(kdst)); glds16(ksn+(long)KVBLK*PIN,(unsigned)__builtin_amdgcn_readfirstlane(kdst+SLOTB)); glds16(ksn+(long)2*KVBLK*PIN,(unsigned)__builtin_amdgcn_readfirstlane(kdst+2*SLOTB));
;     const bf16*Qwn=qkvb+qo+(long)(wid*QBLK)*PIN;
;     _Pragma("unroll") for(int d0=0;d0<4;++d0)qr[d0]=*reinterpret_cast<const bf16x8*>(&Qwn[(long)r32*PIN+d0*16+hi*8]); }
.LBB0_609:
	s_or_b64 exec, exec, s[40:41]
	s_add_i32 s85, s85, 1
	s_cmp_eq_u32 s85, 4
	s_cselect_b32 s85, 8, s85
	s_cmp_eq_u32 s85, 12
	s_cselect_b64 s[40:41], -1, 0
	s_and_b64 s[38:39], s[40:41], exec
	v_readlane_b32 s38, v253, 0
	s_cselect_b32 s43, s38, 0
	s_cselect_b32 s4, 0, s85
	s_add_i32 s43, s43, s75
	s_cmpk_lt_i32 s43, 0x100
	s_cselect_b32 s48, s4, -1
	v_readlane_b32 s39, v253, 1
	s_cmp_gt_i32 s48, -1
	s_cselect_b64 s[38:39], -1, 0
	s_cmp_lt_i32 s48, 0
	s_cbranch_scc1 .LBB0_621
	s_cmp_gt_u32 s48, 7
	s_mov_b64 s[66:67], -1
	s_cbranch_scc0 .LBB0_612
	s_lshl_b32 s4, s43, 2
	s_add_i32 s4, s4, s48
	s_add_i32 s45, s4, -8
	s_and_b32 s42, s45, 127
	s_add_i32 s4, s42, -3
	s_max_i32 s4, s4, 0
	s_ashr_i32 s44, s45, 8
	s_lshl_b64 s[62:63], s[4:5], 6
	s_bfe_u32 s45, s45, 0x10007
	v_readfirstlane_b32 s4, v234
	s_lshr_b32 s4, s4, 6
	s_and_b32 s101, s4, 3
	s_lshr_b32 s100, s4, 2
	s_lshl_b32 s100, s100, 5
	s_lshl_b32 s4, s45, 2
	s_or_b32 s4, s4, s101
	s_lshl_b32 s4, s4, 6
	s_lshl_b32 s45, s45, 6
	s_or_b32 s64, s45, 0x200
	s_mov_b32 s101, 6
	s_mov_b64 s[66:67], 0

;   #define PIN(x) asm volatile("":"+v"(x))
; template<int THRL> __device__ __forceinline__ void attn_unit(long rowbase,int qb,int t0,bool WIN,bool NOMAX,const bf16*Qc,const bf16*__restrict__ Kc,const bf16*__restrict__ Vc,bf16*Oc,float s2,float sink2,char*shm,
;     bf16x8 (&qr)[4],bool pref,const bf16*qkvb,int vn,int in_){
;     ...
;   if(in_>=0){ long qo,ko; unit_qk_offsets(vn,in_,qo,ko);
;     const bf16*ksn=qkvb+ko+(long)lane*PIN+wid*8;
;     glds16(ksn,(unsigned)__builtin_amdgcn_readfirstlane(kdst)); glds16(ksn+(long)KVBLK*PIN,(unsigned)__builtin_amdgcn_readfirstlane(kdst+SLOTB)); glds16(ksn+(long)2*KVBLK*PIN,(unsigned)__builtin_amdgcn_readfirstlane(kdst+2*SLOTB));
;     const bf16*Qwn=qkvb+qo+(long)(wid*QBLK)*PIN;
;     _Pragma("unroll") for(int d0=0;d0<4;++d0)qr[d0]=*reinterpret_cast<const bf16x8*>(&Qwn[(long)r32*PIN+d0*16+hi*8]); }
.LBB0_619:
	s_lshl_b32 s44, s43, 2
	s_ashr_i32 s4, s43, 3
	s_and_b32 s44, s44, 32
	s_add_i32 s44, s44, s4
	s_lshl_b32 s43, s43, 2
	s_lshl_b32 s4, s4, 5
	s_and_b32 s43, s43, 0x180
	s_and_b32 s4, s4, 64
	s_or_b32 s43, s43, s4
	s_ashr_i32 s44, s44, 4
	s_add_i32 s4, s43, 0x300
	s_add_i32 s64, s43, 0x500
	s_mov_b64 s[62:63], 0
	s_lshl_b32 s100, s80, 5
	s_mov_b32 s101, 8
.LBB0_620:
	s_ashr_i32 s45, s44, 31
	s_mov_b32 s43, s5
	s_lshl_b64 s[44:45], s[44:45], 13
	s_lshl_b64 s[42:43], s[42:43], s101
	s_add_u32 s48, s42, s44
	s_addc_u32 s49, s43, s45
	s_add_u32 s42, s62, s44
	s_addc_u32 s43, s63, s45
	s_mulk_i32 s43, 0x1200
	s_mul_hi_u32 s44, s42, 0x1200
	s_add_i32 s44, s44, s43
	s_mulk_i32 s42, 0x1200
	s_mov_b32 s65, s5
	s_add_u32 s45, s72, s42
	s_addc_u32 s44, s73, s44
	s_lshl_b64 s[42:43], s[64:65], 1
	s_add_u32 s42, s45, s42
	s_addc_u32 s43, s44, s43
	v_lshl_add_u64 v[2:3], s[42:43], 0, v[0:1]
	v_lshl_add_u64 v[2:3], s[60:61], 1, v[2:3]
	s_mov_b32 s42, m0
	s_mov_b32 m0, s50
	s_nop 0
	global_load_lds_dwordx4 v[2:3], off
	s_mov_b32 m0, s42
	s_cmp_lg_u32 0, -1
	s_cselect_b32 s42, 0, 0
	s_add_i32 s42, s42, s82
	v_lshl_add_u64 v[4:5], v[2:3], 0, s[6:7]
	s_add_i32 s43, s42, 0x2000
	s_mov_b32 s44, m0
	s_mov_b32 m0, s43
	s_nop 0
	global_load_lds_dwordx4 v[4:5], off
	s_mov_b32 m0, s44
	s_addk_i32 s42, 0x4000
	v_lshl_add_u64 v[2:3], v[2:3], 0, s[0:1]
	s_mov_b32 s43, m0
	s_mov_b32 m0, s42
	s_nop 0
	global_load_lds_dwordx4 v[2:3], off
	s_mov_b32 m0, s43
	s_mulk_i32 s49, 0x1200
	s_mul_hi_u32 s42, s48, 0x1200
	s_add_i32 s42, s42, s49
	s_mulk_i32 s48, 0x1200
	s_add_u32 s44, s72, s48
	s_addc_u32 s45, s73, s42
	s_lshl_b64 s[42:43], s[4:5], 1
	s_add_u32 s4, s44, s42
	s_addc_u32 s43, s45, s43
	s_mul_hi_i32 s44, s100, 0x1200
	s_mulk_i32 s100, 0x1200
	s_add_u32 s42, s4, s100
	s_addc_u32 s43, s43, s44
	v_lshl_or_b32 v0, v181, 4, v222
	global_load_dwordx4 v[2:5], v0, s[42:43]
	global_load_dwordx4 v[6:9], v0, s[42:43] offset:32
	global_load_dwordx4 v[10:13], v0, s[42:43] offset:64
	global_load_dwordx4 v[14:17], v0, s[42:43] offset:96
